# ret_out tail: 8-byte row-per-lane output stores transposed through wave-private LDS into 4 coalesced dwordx4 stores per lane
# speedup vs baseline: 1.0404x; 1.0088x over previous
.LBB0_871:
	s_or_b64 exec, exec, s[0:1]
	v_lshlrev_b32_e32 v15, 7, v169
	v_lshlrev_b64 v[16:17], 1, v[174:175]
	v_or_b32_e32 v14, v171, v192
	s_waitcnt lgkmcnt(0)
	v_lshl_add_u64 v[12:13], s[10:11], 0, v[16:17]
	v_lshlrev_b32_e32 v0, 1, v15
	v_lshlrev_b32_e32 v30, 2, v15
	v_ashrrev_i32_e32 v15, 31, v14
	v_lshl_add_u64 v[12:13], v[12:13], 0, v[0:1]
	v_lshlrev_b64 v[52:53], 1, v[14:15]
	v_lshl_add_u64 v[56:57], v[12:13], 0, v[52:53]
	s_barrier
	global_load_dwordx2 v[64:65], v[56:57], off
	v_mov_b32_e32 v31, v1
	v_lshl_add_u64 v[30:31], s[68:69], 0, v[30:31]
	v_lshl_add_u64 v[60:61], v[14:15], 2, v[30:31]
	global_load_dwordx4 v[12:15], v[60:61], off
	global_load_dwordx2 v[72:73], v[56:57], off offset:16
	global_load_dwordx4 v[30:33], v[60:61], off offset:32
	global_load_dwordx2 v[74:75], v[56:57], off offset:32
	global_load_dwordx4 v[40:43], v[60:61], off offset:64
	global_load_dwordx2 v[76:77], v[56:57], off offset:48
	global_load_dwordx4 v[44:47], v[60:61], off offset:96
	global_load_dwordx2 v[78:79], v[56:57], off offset:64
	global_load_dwordx4 v[48:51], v[60:61], off offset:128
	v_xor_b32_e32 v10, 64, v10
	v_lshl_add_u32 v54, v10, 2, v182
	ds_read_b32 v58, v11
	ds_read_b32 v59, v54
	v_lshl_add_u64 v[10:11], s[12:13], 0, v[16:17]
	v_lshl_add_u64 v[10:11], v[10:11], 0, v[0:1]
	global_load_dwordx2 v[16:17], v[56:57], off offset:80
	v_lshl_add_u64 v[10:11], v[10:11], 0, v[52:53]
	global_load_dwordx4 v[52:55], v[60:61], off offset:160
	s_waitcnt lgkmcnt(0)
	v_add_f32_e32 v0, v58, v59
	v_fmamk_f32 v0, v0, 0x3c000000, v186
	v_mul_f32_e32 v58, 0x4b800000, v0
	v_cmp_gt_f32_e32 vcc, s35, v0
	s_waitcnt vmcnt(11)
	v_and_b32_e32 v85, 0xffff0000, v64
	v_cndmask_b32_e32 v0, v0, v58, vcc
	global_load_dwordx2 v[80:81], v[56:57], off offset:96
	global_load_dwordx2 v[82:83], v[56:57], off offset:112
	s_nop 0
	global_load_dwordx4 v[56:59], v[60:61], off offset:192
	s_nop 0
	global_load_dwordx4 v[60:63], v[60:61], off offset:224
	v_rsq_f32_e32 v0, v0
	s_nop 0
	v_mul_f32_e32 v84, 0x45800000, v0
	v_cndmask_b32_e32 v0, v0, v84, vcc
	v_pk_mul_f32 v[66:67], v[66:67], v[0:1] op_sel_hi:[1,0]
	v_pk_mul_f32 v[68:69], v[68:69], v[0:1] op_sel_hi:[1,0]
	v_pk_mul_f32 v[70:71], v[70:71], v[0:1] op_sel_hi:[1,0]
	v_pk_mul_f32 v[38:39], v[38:39], v[0:1] op_sel_hi:[1,0]
	v_pk_mul_f32 v[36:37], v[36:37], v[0:1] op_sel_hi:[1,0]
	v_pk_mul_f32 v[34:35], v[34:35], v[0:1] op_sel_hi:[1,0]
	v_lshlrev_b32_e32 v84, 16, v64
	s_waitcnt vmcnt(14)
	v_pk_mul_f32 v[12:13], v[12:13], v[66:67]
	v_and_b32_e32 v67, 0xffff0000, v65
	v_lshlrev_b32_e32 v66, 16, v65
	v_pk_mul_f32 v[14:15], v[14:15], v[68:69]
	s_waitcnt vmcnt(13)
	v_and_b32_e32 v65, 0xffff0000, v72
	v_lshlrev_b32_e32 v64, 16, v72
	s_waitcnt vmcnt(12)
	v_pk_mul_f32 v[30:31], v[30:31], v[70:71]
	v_and_b32_e32 v69, 0xffff0000, v73
	v_lshlrev_b32_e32 v68, 16, v73
	v_pk_mul_f32 v[32:33], v[32:33], v[38:39]
	s_waitcnt vmcnt(11)
	v_and_b32_e32 v39, 0xffff0000, v74
	v_lshlrev_b32_e32 v38, 16, v74
	s_waitcnt vmcnt(10)
	v_pk_mul_f32 v[36:37], v[40:41], v[36:37]
	v_and_b32_e32 v41, 0xffff0000, v75
	v_lshlrev_b32_e32 v40, 16, v75
	v_pk_mul_f32 v[34:35], v[42:43], v[34:35]
	v_pk_mul_f32 v[12:13], v[12:13], v[84:85]
	v_pk_mul_f32 v[14:15], v[14:15], v[66:67]
	v_pk_mul_f32 v[30:31], v[30:31], v[64:65]
	v_pk_mul_f32 v[32:33], v[32:33], v[68:69]
	v_pk_mul_f32 v[36:37], v[36:37], v[38:39]
	v_pk_mul_f32 v[34:35], v[34:35], v[40:41]
	v_cvt_pk_bf16_f32 v12, v12, v13
	v_cvt_pk_bf16_f32 v13, v14, v15
	v_cvt_pk_bf16_f32 v14, v30, v31
	v_cvt_pk_bf16_f32 v15, v32, v33
	v_cvt_pk_bf16_f32 v30, v36, v37
	v_cvt_pk_bf16_f32 v31, v34, v35
	v_and_b32_e32 v233, 63, v172
	v_lshrrev_b32_e32 v232, 6, v172
	v_mul_u32_u24_e32 v232, 0x1200, v232
	v_add_u32_e32 v232, v232, v182
	v_add_u32_e32 v232, 0x800, v232
	v_and_b32_e32 v244, 31, v233
	v_lshrrev_b32_e32 v245, 5, v233
	v_lshrrev_b32_e32 v246, 3, v233
	v_and_b32_e32 v247, 7, v233
	v_mul_u32_u24_e32 v248, 0x90, v246
	v_lshl_add_u32 v248, v247, 4, v248
	v_add_u32_e32 v233, v248, v232
	v_mul_u32_u24_e32 v248, 0x90, v244
	v_lshl_add_u32 v248, v245, 3, v248
	v_add_u32_e32 v232, v248, v232
	v_sub_u32_e32 v246, v246, v244
	v_lshlrev_b32_e32 v246, 11, v246
	v_lshl_add_u32 v246, v247, 4, v246
	v_lshlrev_b32_e32 v245, 3, v245
	v_sub_u32_e32 v246, v246, v245
	v_ashrrev_i32_e32 v247, 31, v246
	v_lshl_add_u64 v[244:245], v[10:11], 0, v[246:247]
	ds_write_b64 v232, v[12:13]
	ds_write_b64 v232, v[14:15] offset:16
	ds_write_b64 v232, v[30:31] offset:32
	v_pk_mul_f32 v[12:13], v[24:25], v[0:1] op_sel_hi:[1,0]
	v_pk_mul_f32 v[22:23], v[22:23], v[0:1] op_sel_hi:[1,0]
	s_waitcnt vmcnt(9)
	v_and_b32_e32 v43, 0xffff0000, v76
	v_lshlrev_b32_e32 v42, 16, v76
	s_waitcnt vmcnt(8)
	v_pk_mul_f32 v[12:13], v[12:13], v[44:45]
	v_and_b32_e32 v15, 0xffff0000, v77
	v_lshlrev_b32_e32 v14, 16, v77
	v_pk_mul_f32 v[22:23], v[22:23], v[46:47]
	v_pk_mul_f32 v[12:13], v[12:13], v[42:43]
	v_pk_mul_f32 v[14:15], v[22:23], v[14:15]
	v_cvt_pk_bf16_f32 v12, v12, v13
	v_cvt_pk_bf16_f32 v13, v14, v15
	v_pk_mul_f32 v[14:15], v[28:29], v[0:1] op_sel_hi:[1,0]
	ds_write_b64 v232, v[12:13] offset:48
	s_waitcnt vmcnt(7)
	v_and_b32_e32 v13, 0xffff0000, v78
	v_lshlrev_b32_e32 v12, 16, v78
	s_waitcnt vmcnt(6)
	v_pk_mul_f32 v[14:15], v[14:15], v[48:49]
	v_pk_mul_f32 v[22:23], v[26:27], v[0:1] op_sel_hi:[1,0]
	v_pk_mul_f32 v[12:13], v[14:15], v[12:13]
	v_and_b32_e32 v15, 0xffff0000, v79
	v_lshlrev_b32_e32 v14, 16, v79
	v_pk_mul_f32 v[22:23], v[22:23], v[50:51]
	v_cvt_pk_bf16_f32 v12, v12, v13
	v_pk_mul_f32 v[14:15], v[22:23], v[14:15]
	v_pk_mul_f32 v[8:9], v[8:9], v[0:1] op_sel_hi:[1,0]
	v_cvt_pk_bf16_f32 v13, v14, v15
	v_pk_mul_f32 v[14:15], v[20:21], v[0:1] op_sel_hi:[1,0]
	ds_write_b64 v232, v[12:13] offset:64
	s_waitcnt vmcnt(5)
	v_and_b32_e32 v13, 0xffff0000, v16
	v_lshlrev_b32_e32 v12, 16, v16
	s_waitcnt vmcnt(4)
	v_pk_mul_f32 v[14:15], v[14:15], v[52:53]
	v_pk_mul_f32 v[6:7], v[6:7], v[0:1] op_sel_hi:[1,0]
	v_pk_mul_f32 v[12:13], v[14:15], v[12:13]
	v_and_b32_e32 v15, 0xffff0000, v17
	v_lshlrev_b32_e32 v14, 16, v17
	v_pk_mul_f32 v[16:17], v[18:19], v[0:1] op_sel_hi:[1,0]
	v_cvt_pk_bf16_f32 v12, v12, v13
	v_pk_mul_f32 v[16:17], v[16:17], v[54:55]
	s_waitcnt vmcnt(1)
	v_pk_mul_f32 v[8:9], v[8:9], v[56:57]
	v_pk_mul_f32 v[14:15], v[16:17], v[14:15]
	v_pk_mul_f32 v[6:7], v[6:7], v[58:59]
	v_cvt_pk_bf16_f32 v13, v14, v15
	ds_write_b64 v232, v[12:13] offset:80
	v_and_b32_e32 v13, 0xffff0000, v80
	v_lshlrev_b32_e32 v12, 16, v80
	v_pk_mul_f32 v[8:9], v[8:9], v[12:13]
	v_and_b32_e32 v13, 0xffff0000, v81
	v_lshlrev_b32_e32 v12, 16, v81
	v_pk_mul_f32 v[6:7], v[6:7], v[12:13]
	v_pk_mul_f32 v[4:5], v[4:5], v[0:1] op_sel_hi:[1,0]
	v_cvt_pk_bf16_f32 v8, v8, v9
	v_cvt_pk_bf16_f32 v9, v6, v7
	v_and_b32_e32 v7, 0xffff0000, v82
	v_lshlrev_b32_e32 v6, 16, v82
	s_waitcnt vmcnt(0)
	v_pk_mul_f32 v[4:5], v[4:5], v[60:61]
	v_pk_mul_f32 v[2:3], v[2:3], v[0:1] op_sel_hi:[1,0]
	v_pk_mul_f32 v[4:5], v[4:5], v[6:7]
	v_and_b32_e32 v7, 0xffff0000, v83
	v_lshlrev_b32_e32 v6, 16, v83
	v_pk_mul_f32 v[2:3], v[2:3], v[62:63]
	v_cvt_pk_bf16_f32 v4, v4, v5
	v_pk_mul_f32 v[2:3], v[2:3], v[6:7]
	ds_write_b64 v232, v[8:9] offset:96
	v_cvt_pk_bf16_f32 v5, v2, v3
	ds_write_b64 v232, v[4:5] offset:112
	s_waitcnt lgkmcnt(0)
	ds_read_b128 v[200:203], v233
	ds_read_b128 v[204:207], v233 offset:1152
	ds_read_b128 v[208:211], v233 offset:2304
	ds_read_b128 v[212:215], v233 offset:3456
	v_mov_b32_e32 v246, 0x4000
	v_mov_b32_e32 v247, 0
	s_waitcnt lgkmcnt(3)
	global_store_dwordx4 v[244:245], v[200:203], off
	v_lshl_add_u64 v[244:245], v[244:245], 0, v[246:247]
	s_waitcnt lgkmcnt(2)
	global_store_dwordx4 v[244:245], v[204:207], off
	v_lshl_add_u64 v[244:245], v[244:245], 0, v[246:247]
	s_waitcnt lgkmcnt(1)
	global_store_dwordx4 v[244:245], v[208:211], off
	v_lshl_add_u64 v[244:245], v[244:245], 0, v[246:247]
	s_waitcnt lgkmcnt(0)
	global_store_dwordx4 v[244:245], v[212:215], off
